# S5 full pass: the four C-matrix fragment load pairs issued together (one wait instead of four)
# speedup vs baseline: 1.0080x; 1.0004x over previous
.LBB0_437:
	s_lshl_b64 s[2:3], s[34:35], 4
	v_mov_b32_e32 v41, s3
	v_or_b32_e32 v40, s2, v78
	v_lshlrev_b64 v[44:45], 8, v[40:41]
	v_readlane_b32 s56, v252, 18
	v_lshl_or_b32 v44, v80, 2, v44
	v_readlane_b32 s62, v252, 24
	v_readlane_b32 s63, v252, 25
	v_readlane_b32 s60, v252, 22
	v_readlane_b32 s61, v252, 23
	v_lshl_add_u64 v[96:97], s[62:63], 0, v[44:45]
	s_lshl_b32 s2, s28, 4
	v_lshl_add_u64 v[94:95], s[60:61], 0, v[44:45]
	global_load_dwordx4 v[44:47], v[96:97], off offset:192
	global_load_dwordx4 v[40:43], v[94:95], off offset:192
	global_load_dwordx4 v[136:139], v[94:95], off offset:128
	global_load_dwordx4 v[140:143], v[96:97], off offset:128
	global_load_dwordx4 v[144:147], v[94:95], off offset:64
	global_load_dwordx4 v[148:151], v[96:97], off offset:64
	global_load_dwordx4 v[152:155], v[94:95], off
	global_load_dwordx4 v[156:159], v[96:97], off
	v_readlane_b32 s64, v252, 26
	v_readlane_b32 s65, v252, 27
	v_readlane_b32 s68, v252, 30
	v_readlane_b32 s69, v252, 31
	v_readlane_b32 s70, v252, 32
	v_readlane_b32 s71, v252, 33
	s_ashr_i32 s3, s2, 31
	s_xor_b64 s[0:1], s[30:31], -1
	s_mov_b32 s14, 0
	s_waitcnt vmcnt(0) lgkmcnt(0)
	v_cndmask_b32_e64 v11, v11, 0, s[8:9]
	v_cndmask_b32_e64 v10, v10, 0, s[8:9]
	v_cndmask_b32_e64 v9, v9, 0, s[8:9]
	v_cndmask_b32_e64 v8, v8, 0, s[8:9]
	v_cndmask_b32_e64 v15, v15, 0, s[8:9]
	v_cndmask_b32_e64 v14, v14, 0, s[8:9]
	v_cndmask_b32_e64 v13, v13, 0, s[8:9]
	v_cndmask_b32_e64 v12, v12, 0, s[8:9]
	v_cndmask_b32_e64 v19, v19, 0, s[8:9]
	v_cndmask_b32_e64 v18, v18, 0, s[8:9]
	v_cndmask_b32_e64 v17, v17, 0, s[8:9]
	v_cndmask_b32_e64 v16, v16, 0, s[8:9]
	v_cndmask_b32_e64 v23, v23, 0, s[8:9]
	v_cndmask_b32_e64 v22, v22, 0, s[8:9]
	v_cndmask_b32_e64 v21, v21, 0, s[8:9]
	v_cndmask_b32_e64 v20, v20, 0, s[8:9]
	v_cndmask_b32_e64 v27, v27, 0, s[8:9]
	v_cndmask_b32_e64 v26, v26, 0, s[8:9]
	v_cndmask_b32_e64 v25, v25, 0, s[8:9]
	v_cndmask_b32_e64 v24, v24, 0, s[8:9]
	v_cndmask_b32_e64 v31, v31, 0, s[8:9]
	v_cndmask_b32_e64 v30, v30, 0, s[8:9]
	v_cndmask_b32_e64 v29, v29, 0, s[8:9]
	v_cndmask_b32_e64 v28, v28, 0, s[8:9]
	v_cndmask_b32_e64 v35, v35, 0, s[8:9]
	v_cndmask_b32_e64 v34, v34, 0, s[8:9]
	v_cndmask_b32_e64 v33, v33, 0, s[8:9]
	v_cndmask_b32_e64 v32, v32, 0, s[8:9]
	v_cndmask_b32_e64 v39, v39, 0, s[8:9]
	v_cndmask_b32_e64 v38, v38, 0, s[8:9]
	v_cndmask_b32_e64 v37, v37, 0, s[8:9]
	v_cndmask_b32_e64 v36, v36, 0, s[8:9]
	v_lshl_add_u32 v120, s28, 5, v108
	v_pk_mov_b32 v[98:99], v[90:91], v[90:91] op_sel:[1,0]
	s_mov_b64 s[4:5], -1
	s_lshl_b64 s[10:11], s[2:3], 1
	v_readlane_b32 s65, v255, 11
	v_readlane_b32 s64, v255, 12
	s_movk_i32 s62, 0x7fff
	s_movk_i32 s15, 0x210
	s_mov_b64 s[70:71], 0x80
	s_mov_b64 s[68:69], 0xc00
	s_mov_b32 s56, s96
	v_readlane_b32 s57, v252, 19
	v_readlane_b32 s58, v252, 20
	v_readlane_b32 s59, v252, 21
	v_readlane_b32 s66, v252, 28
	v_readlane_b32 s67, v252, 29
	v_xor_b32_e32 v44, 0x80000000, v44
	v_cvt_pk_bf16_f32 v40, v40, v44
	v_xor_b32_e32 v44, 0x80000000, v45
	v_cvt_pk_bf16_f32 v41, v41, v44
	v_xor_b32_e32 v44, 0x80000000, v46
	v_cvt_pk_bf16_f32 v42, v42, v44
	v_xor_b32_e32 v44, 0x80000000, v47
	v_cvt_pk_bf16_f32 v43, v43, v44
	v_xor_b32_e32 v48, 0x80000000, v140
	v_cvt_pk_bf16_f32 v44, v136, v48
	v_xor_b32_e32 v48, 0x80000000, v141
	v_cvt_pk_bf16_f32 v45, v137, v48
	v_xor_b32_e32 v48, 0x80000000, v142
	v_cvt_pk_bf16_f32 v46, v138, v48
	v_xor_b32_e32 v48, 0x80000000, v143
	v_cvt_pk_bf16_f32 v47, v139, v48
	v_xor_b32_e32 v52, 0x80000000, v148
	v_cvt_pk_bf16_f32 v48, v144, v52
	v_xor_b32_e32 v52, 0x80000000, v149
	v_cvt_pk_bf16_f32 v49, v145, v52
	v_xor_b32_e32 v52, 0x80000000, v150
	v_cvt_pk_bf16_f32 v50, v146, v52
	v_xor_b32_e32 v52, 0x80000000, v151
	v_cvt_pk_bf16_f32 v51, v147, v52
	v_xor_b32_e32 v83, 0x80000000, v156
	v_cvt_pk_bf16_f32 v52, v152, v83
	v_xor_b32_e32 v83, 0x80000000, v157
	v_cvt_pk_bf16_f32 v53, v153, v83
	v_xor_b32_e32 v83, 0x80000000, v158
	v_cvt_pk_bf16_f32 v54, v154, v83
	v_xor_b32_e32 v83, 0x80000000, v159
	v_cvt_pk_bf16_f32 v55, v155, v83
	v_mov_b32_e32 v94, v90
	v_mov_b32_e32 v95, v90
	v_mov_b32_e32 v96, v91
	v_mov_b32_e32 v97, v91
